# merge step-2/3 epilogue: rolled gated-combine loop (vmcnt(0) after every 16-byte load) replaced by straight-line code with all MG/TG loads issued up front and counted waits
# speedup vs baseline: 1.0065x; 1.0065x over previous
; DI unsigned pk2(float a, float b) { f32x2 v = {a, b}; return __builtin_bit_cast(unsigned, __builtin_convertvector(v, bf16x2)); }
; DI float bflo(unsigned u) { return __uint_as_float(u << 16); }
; DI float bfhi(unsigned u) { return __uint_as_float(u & 0xffff0000u); }
; DI void phase_merge(const Params& P, int layer, char* smem) {
;     ...
; #pragma unroll 2
;         for (int i = 0; i < 8; ++i) {
;           const int idx = tid_ + 256 * i;
;           const int row = idx >> 4, c8 = (idx & 15) * 8;
;           u32x4* gp = (u32x4*)(MG + (size_t)(m0 + row) * 1024 + n0 + c8);
;           const u32x4 mg = *gp;
;           const u32x4 pj = *(const u32x4*)(Cs + row * 136 + c8);
;           u32x4 ov;
;           if (step == 2) {
; #pragma unroll
;             for (int e = 0; e < 4; ++e) ov[e] = pk2(bflo(mg[e]) * bflo(pj[e]), bfhi(mg[e]) * bfhi(pj[e]));
;           } else {
;             const u32x4 tg = *(const u32x4*)(TG + (size_t)(m0 + row) * 1024 + n0 + c8);
; #pragma unroll
;             for (int e = 0; e < 4; ++e) ov[e] = pk2(bflo(mg[e]) + bflo(tg[e]) * bflo(pj[e]), bfhi(mg[e]) + bfhi(tg[e]) * bfhi(pj[e]));
;           }
;           *gp = ov;
;         }
.LBB0_56:
	v_ashrrev_i32_e32 v64, 4, v94
	v_add_u32_e32 v66, s0, v64
	v_ashrrev_i32_e32 v67, 31, v66
	v_lshlrev_b64 v[66:67], 11, v[66:67]
	v_mad_u32_u24 v65, v64, s97, v136
	s_mov_b64 s[18:19], 0x8000
	v_lshl_add_u64 v[152:153], v[68:69], 0, v[66:67]
	v_lshl_add_u64 v[154:155], v[152:153], 0, s[18:19]
	v_lshl_add_u64 v[156:157], v[154:155], 0, s[18:19]
	v_lshl_add_u64 v[158:159], v[156:157], 0, s[18:19]
	v_lshl_add_u64 v[240:241], v[158:159], 0, s[18:19]
	v_lshl_add_u64 v[242:243], v[240:241], 0, s[18:19]
	v_lshl_add_u64 v[244:245], v[242:243], 0, s[18:19]
	v_lshl_add_u64 v[246:247], v[244:245], 0, s[18:19]
	global_load_dwordx4 v[208:211], v[152:153], off
	global_load_dwordx4 v[212:215], v[154:155], off
	global_load_dwordx4 v[216:219], v[156:157], off
	global_load_dwordx4 v[220:223], v[158:159], off
	global_load_dwordx4 v[224:227], v[240:241], off
	global_load_dwordx4 v[228:231], v[242:243], off
	global_load_dwordx4 v[232:235], v[244:245], off
	global_load_dwordx4 v[236:239], v[246:247], off
	s_and_b64 vcc, exec, s[40:41]
	s_cbranch_vccz .Lmg_step2
	v_lshl_add_u64 v[248:249], v[70:71], 0, v[66:67]
	global_load_dwordx4 v[104:107], v[248:249], off
	v_lshl_add_u64 v[248:249], v[248:249], 0, s[18:19]
	global_load_dwordx4 v[108:111], v[248:249], off
	v_lshl_add_u64 v[248:249], v[248:249], 0, s[18:19]
	global_load_dwordx4 v[112:115], v[248:249], off
	v_lshl_add_u64 v[248:249], v[248:249], 0, s[18:19]
	global_load_dwordx4 v[116:119], v[248:249], off
	v_lshl_add_u64 v[248:249], v[248:249], 0, s[18:19]
	global_load_dwordx4 v[120:123], v[248:249], off
	v_lshl_add_u64 v[248:249], v[248:249], 0, s[18:19]
	global_load_dwordx4 v[124:127], v[248:249], off
	v_lshl_add_u64 v[248:249], v[248:249], 0, s[18:19]
	global_load_dwordx4 v[128:131], v[248:249], off
	v_lshl_add_u64 v[248:249], v[248:249], 0, s[18:19]
	global_load_dwordx4 v[140:143], v[248:249], off
	ds_read_b128 v[72:75], v65
	ds_read_b128 v[76:79], v65 offset:4352
	ds_read_b128 v[80:83], v65 offset:8704
	ds_read_b128 v[84:87], v65 offset:13056
	ds_read_b128 v[88:91], v65 offset:17408
	ds_read_b128 v[92:95], v65 offset:21760
	ds_read_b128 v[144:147], v65 offset:26112
	ds_read_b128 v[148:151], v65 offset:30464
	s_waitcnt vmcnt(7) lgkmcnt(7)
	v_lshlrev_b32_e32 v64, 16, v72
	v_and_b32_e32 v65, 0xffff0000, v72
	v_lshlrev_b32_e32 v66, 16, v208
	v_and_b32_e32 v67, 0xffff0000, v208
	v_lshlrev_b32_e32 v248, 16, v104
	v_and_b32_e32 v249, 0xffff0000, v104
	v_pk_fma_f32 v[248:249], v[64:65], v[248:249], v[66:67]
	s_nop 0
	v_cvt_pk_bf16_f32 v208, v248, v249
	v_lshlrev_b32_e32 v64, 16, v73
	v_and_b32_e32 v65, 0xffff0000, v73
	v_lshlrev_b32_e32 v66, 16, v209
	v_and_b32_e32 v67, 0xffff0000, v209
	v_lshlrev_b32_e32 v248, 16, v105
	v_and_b32_e32 v249, 0xffff0000, v105
	v_pk_fma_f32 v[248:249], v[64:65], v[248:249], v[66:67]
	s_nop 0
	v_cvt_pk_bf16_f32 v209, v248, v249
	v_lshlrev_b32_e32 v64, 16, v74
	v_and_b32_e32 v65, 0xffff0000, v74
	v_lshlrev_b32_e32 v66, 16, v210
	v_and_b32_e32 v67, 0xffff0000, v210
	v_lshlrev_b32_e32 v248, 16, v106
	v_and_b32_e32 v249, 0xffff0000, v106
	v_pk_fma_f32 v[248:249], v[64:65], v[248:249], v[66:67]
	s_nop 0
	v_cvt_pk_bf16_f32 v210, v248, v249
	v_lshlrev_b32_e32 v64, 16, v75
	v_and_b32_e32 v65, 0xffff0000, v75
	v_lshlrev_b32_e32 v66, 16, v211
	v_and_b32_e32 v67, 0xffff0000, v211
	v_lshlrev_b32_e32 v248, 16, v107
	v_and_b32_e32 v249, 0xffff0000, v107
	v_pk_fma_f32 v[248:249], v[64:65], v[248:249], v[66:67]
	s_nop 0
	v_cvt_pk_bf16_f32 v211, v248, v249
	global_store_dwordx4 v[152:153], v[208:211], off
	s_waitcnt vmcnt(7) lgkmcnt(6)
	v_lshlrev_b32_e32 v64, 16, v76
	v_and_b32_e32 v65, 0xffff0000, v76
	v_lshlrev_b32_e32 v66, 16, v212
	v_and_b32_e32 v67, 0xffff0000, v212
	v_lshlrev_b32_e32 v248, 16, v108
	v_and_b32_e32 v249, 0xffff0000, v108
	v_pk_fma_f32 v[248:249], v[64:65], v[248:249], v[66:67]
	s_nop 0
	v_cvt_pk_bf16_f32 v212, v248, v249
	v_lshlrev_b32_e32 v64, 16, v77
	v_and_b32_e32 v65, 0xffff0000, v77
	v_lshlrev_b32_e32 v66, 16, v213
	v_and_b32_e32 v67, 0xffff0000, v213
	v_lshlrev_b32_e32 v248, 16, v109
	v_and_b32_e32 v249, 0xffff0000, v109
	v_pk_fma_f32 v[248:249], v[64:65], v[248:249], v[66:67]
	s_nop 0
	v_cvt_pk_bf16_f32 v213, v248, v249
	v_lshlrev_b32_e32 v64, 16, v78
	v_and_b32_e32 v65, 0xffff0000, v78
	v_lshlrev_b32_e32 v66, 16, v214
	v_and_b32_e32 v67, 0xffff0000, v214
	v_lshlrev_b32_e32 v248, 16, v110
	v_and_b32_e32 v249, 0xffff0000, v110
	v_pk_fma_f32 v[248:249], v[64:65], v[248:249], v[66:67]
	s_nop 0
	v_cvt_pk_bf16_f32 v214, v248, v249
	v_lshlrev_b32_e32 v64, 16, v79
	v_and_b32_e32 v65, 0xffff0000, v79
	v_lshlrev_b32_e32 v66, 16, v215
	v_and_b32_e32 v67, 0xffff0000, v215
	v_lshlrev_b32_e32 v248, 16, v111
	v_and_b32_e32 v249, 0xffff0000, v111
	v_pk_fma_f32 v[248:249], v[64:65], v[248:249], v[66:67]
	s_nop 0
	v_cvt_pk_bf16_f32 v215, v248, v249
	global_store_dwordx4 v[154:155], v[212:215], off
	s_waitcnt vmcnt(7) lgkmcnt(5)
	v_lshlrev_b32_e32 v64, 16, v80
	v_and_b32_e32 v65, 0xffff0000, v80
	v_lshlrev_b32_e32 v66, 16, v216
	v_and_b32_e32 v67, 0xffff0000, v216
	v_lshlrev_b32_e32 v248, 16, v112
	v_and_b32_e32 v249, 0xffff0000, v112
	v_pk_fma_f32 v[248:249], v[64:65], v[248:249], v[66:67]
	s_nop 0
	v_cvt_pk_bf16_f32 v216, v248, v249
	v_lshlrev_b32_e32 v64, 16, v81
	v_and_b32_e32 v65, 0xffff0000, v81
	v_lshlrev_b32_e32 v66, 16, v217
	v_and_b32_e32 v67, 0xffff0000, v217
	v_lshlrev_b32_e32 v248, 16, v113
	v_and_b32_e32 v249, 0xffff0000, v113
	v_pk_fma_f32 v[248:249], v[64:65], v[248:249], v[66:67]
	s_nop 0
	v_cvt_pk_bf16_f32 v217, v248, v249
	v_lshlrev_b32_e32 v64, 16, v82
	v_and_b32_e32 v65, 0xffff0000, v82
	v_lshlrev_b32_e32 v66, 16, v218
	v_and_b32_e32 v67, 0xffff0000, v218
	v_lshlrev_b32_e32 v248, 16, v114
	v_and_b32_e32 v249, 0xffff0000, v114
	v_pk_fma_f32 v[248:249], v[64:65], v[248:249], v[66:67]
	s_nop 0
	v_cvt_pk_bf16_f32 v218, v248, v249
	v_lshlrev_b32_e32 v64, 16, v83
	v_and_b32_e32 v65, 0xffff0000, v83
	v_lshlrev_b32_e32 v66, 16, v219
	v_and_b32_e32 v67, 0xffff0000, v219
	v_lshlrev_b32_e32 v248, 16, v115
	v_and_b32_e32 v249, 0xffff0000, v115
	v_pk_fma_f32 v[248:249], v[64:65], v[248:249], v[66:67]
	s_nop 0
	v_cvt_pk_bf16_f32 v219, v248, v249
	global_store_dwordx4 v[156:157], v[216:219], off
	s_waitcnt vmcnt(7) lgkmcnt(4)
; DI unsigned pk2(float a, float b) { f32x2 v = {a, b}; return __builtin_bit_cast(unsigned, __builtin_convertvector(v, bf16x2)); }
; DI float bflo(unsigned u) { return __uint_as_float(u << 16); }
; DI float bfhi(unsigned u) { return __uint_as_float(u & 0xffff0000u); }
; DI void phase_merge(const Params& P, int layer, char* smem) {
;     ...
; #pragma unroll 2
;         for (int i = 0; i < 8; ++i) {
;           const int idx = tid_ + 256 * i;
;           const int row = idx >> 4, c8 = (idx & 15) * 8;
;           u32x4* gp = (u32x4*)(MG + (size_t)(m0 + row) * 1024 + n0 + c8);
;           const u32x4 mg = *gp;
;           const u32x4 pj = *(const u32x4*)(Cs + row * 136 + c8);
;           u32x4 ov;
;           if (step == 2) {
; #pragma unroll
;             for (int e = 0; e < 4; ++e) ov[e] = pk2(bflo(mg[e]) * bflo(pj[e]), bfhi(mg[e]) * bfhi(pj[e]));
;           } else {
;             const u32x4 tg = *(const u32x4*)(TG + (size_t)(m0 + row) * 1024 + n0 + c8);
; #pragma unroll
;             for (int e = 0; e < 4; ++e) ov[e] = pk2(bflo(mg[e]) + bflo(tg[e]) * bflo(pj[e]), bfhi(mg[e]) + bfhi(tg[e]) * bfhi(pj[e]));
;           }
;           *gp = ov;
;         }
	v_lshlrev_b32_e32 v64, 16, v84
	v_and_b32_e32 v65, 0xffff0000, v84
	v_lshlrev_b32_e32 v66, 16, v220
	v_and_b32_e32 v67, 0xffff0000, v220
	v_lshlrev_b32_e32 v248, 16, v116
	v_and_b32_e32 v249, 0xffff0000, v116
	v_pk_fma_f32 v[248:249], v[64:65], v[248:249], v[66:67]
	s_nop 0
	v_cvt_pk_bf16_f32 v220, v248, v249
	v_lshlrev_b32_e32 v64, 16, v85
	v_and_b32_e32 v65, 0xffff0000, v85
	v_lshlrev_b32_e32 v66, 16, v221
	v_and_b32_e32 v67, 0xffff0000, v221
	v_lshlrev_b32_e32 v248, 16, v117
	v_and_b32_e32 v249, 0xffff0000, v117
	v_pk_fma_f32 v[248:249], v[64:65], v[248:249], v[66:67]
	s_nop 0
	v_cvt_pk_bf16_f32 v221, v248, v249
	v_lshlrev_b32_e32 v64, 16, v86
	v_and_b32_e32 v65, 0xffff0000, v86
	v_lshlrev_b32_e32 v66, 16, v222
	v_and_b32_e32 v67, 0xffff0000, v222
	v_lshlrev_b32_e32 v248, 16, v118
	v_and_b32_e32 v249, 0xffff0000, v118
	v_pk_fma_f32 v[248:249], v[64:65], v[248:249], v[66:67]
	s_nop 0
	v_cvt_pk_bf16_f32 v222, v248, v249
	v_lshlrev_b32_e32 v64, 16, v87
	v_and_b32_e32 v65, 0xffff0000, v87
	v_lshlrev_b32_e32 v66, 16, v223
	v_and_b32_e32 v67, 0xffff0000, v223
	v_lshlrev_b32_e32 v248, 16, v119
	v_and_b32_e32 v249, 0xffff0000, v119
	v_pk_fma_f32 v[248:249], v[64:65], v[248:249], v[66:67]
	s_nop 0
	v_cvt_pk_bf16_f32 v223, v248, v249
	global_store_dwordx4 v[158:159], v[220:223], off
	s_waitcnt vmcnt(7) lgkmcnt(3)
	v_lshlrev_b32_e32 v64, 16, v88
	v_and_b32_e32 v65, 0xffff0000, v88
	v_lshlrev_b32_e32 v66, 16, v224
	v_and_b32_e32 v67, 0xffff0000, v224
	v_lshlrev_b32_e32 v248, 16, v120
	v_and_b32_e32 v249, 0xffff0000, v120
	v_pk_fma_f32 v[248:249], v[64:65], v[248:249], v[66:67]
	s_nop 0
	v_cvt_pk_bf16_f32 v224, v248, v249
	v_lshlrev_b32_e32 v64, 16, v89
	v_and_b32_e32 v65, 0xffff0000, v89
	v_lshlrev_b32_e32 v66, 16, v225
	v_and_b32_e32 v67, 0xffff0000, v225
	v_lshlrev_b32_e32 v248, 16, v121
	v_and_b32_e32 v249, 0xffff0000, v121
	v_pk_fma_f32 v[248:249], v[64:65], v[248:249], v[66:67]
	s_nop 0
	v_cvt_pk_bf16_f32 v225, v248, v249
	v_lshlrev_b32_e32 v64, 16, v90
	v_and_b32_e32 v65, 0xffff0000, v90
	v_lshlrev_b32_e32 v66, 16, v226
	v_and_b32_e32 v67, 0xffff0000, v226
	v_lshlrev_b32_e32 v248, 16, v122
	v_and_b32_e32 v249, 0xffff0000, v122
	v_pk_fma_f32 v[248:249], v[64:65], v[248:249], v[66:67]
	s_nop 0
	v_cvt_pk_bf16_f32 v226, v248, v249
	v_lshlrev_b32_e32 v64, 16, v91
	v_and_b32_e32 v65, 0xffff0000, v91
	v_lshlrev_b32_e32 v66, 16, v227
	v_and_b32_e32 v67, 0xffff0000, v227
	v_lshlrev_b32_e32 v248, 16, v123
	v_and_b32_e32 v249, 0xffff0000, v123
	v_pk_fma_f32 v[248:249], v[64:65], v[248:249], v[66:67]
	s_nop 0
	v_cvt_pk_bf16_f32 v227, v248, v249
	global_store_dwordx4 v[240:241], v[224:227], off
	s_waitcnt vmcnt(7) lgkmcnt(2)
	v_lshlrev_b32_e32 v64, 16, v92
	v_and_b32_e32 v65, 0xffff0000, v92
	v_lshlrev_b32_e32 v66, 16, v228
	v_and_b32_e32 v67, 0xffff0000, v228
	v_lshlrev_b32_e32 v248, 16, v124
	v_and_b32_e32 v249, 0xffff0000, v124
	v_pk_fma_f32 v[248:249], v[64:65], v[248:249], v[66:67]
	s_nop 0
	v_cvt_pk_bf16_f32 v228, v248, v249
	v_lshlrev_b32_e32 v64, 16, v93
	v_and_b32_e32 v65, 0xffff0000, v93
	v_lshlrev_b32_e32 v66, 16, v229
	v_and_b32_e32 v67, 0xffff0000, v229
	v_lshlrev_b32_e32 v248, 16, v125
	v_and_b32_e32 v249, 0xffff0000, v125
	v_pk_fma_f32 v[248:249], v[64:65], v[248:249], v[66:67]
	s_nop 0
	v_cvt_pk_bf16_f32 v229, v248, v249
	v_lshlrev_b32_e32 v64, 16, v94
	v_and_b32_e32 v65, 0xffff0000, v94
	v_lshlrev_b32_e32 v66, 16, v230
	v_and_b32_e32 v67, 0xffff0000, v230
	v_lshlrev_b32_e32 v248, 16, v126
	v_and_b32_e32 v249, 0xffff0000, v126
	v_pk_fma_f32 v[248:249], v[64:65], v[248:249], v[66:67]
	s_nop 0
	v_cvt_pk_bf16_f32 v230, v248, v249
	v_lshlrev_b32_e32 v64, 16, v95
	v_and_b32_e32 v65, 0xffff0000, v95
	v_lshlrev_b32_e32 v66, 16, v231
	v_and_b32_e32 v67, 0xffff0000, v231
	v_lshlrev_b32_e32 v248, 16, v127
	v_and_b32_e32 v249, 0xffff0000, v127
	v_pk_fma_f32 v[248:249], v[64:65], v[248:249], v[66:67]
	s_nop 0
	v_cvt_pk_bf16_f32 v231, v248, v249
	global_store_dwordx4 v[242:243], v[228:231], off
	s_waitcnt vmcnt(7) lgkmcnt(1)
	v_lshlrev_b32_e32 v64, 16, v144
	v_and_b32_e32 v65, 0xffff0000, v144
	v_lshlrev_b32_e32 v66, 16, v232
	v_and_b32_e32 v67, 0xffff0000, v232
	v_lshlrev_b32_e32 v248, 16, v128
	v_and_b32_e32 v249, 0xffff0000, v128
	v_pk_fma_f32 v[248:249], v[64:65], v[248:249], v[66:67]
	s_nop 0
	v_cvt_pk_bf16_f32 v232, v248, v249
	v_lshlrev_b32_e32 v64, 16, v145
	v_and_b32_e32 v65, 0xffff0000, v145
	v_lshlrev_b32_e32 v66, 16, v233
	v_and_b32_e32 v67, 0xffff0000, v233
	v_lshlrev_b32_e32 v248, 16, v129
	v_and_b32_e32 v249, 0xffff0000, v129
	v_pk_fma_f32 v[248:249], v[64:65], v[248:249], v[66:67]
	s_nop 0
	v_cvt_pk_bf16_f32 v233, v248, v249
	v_lshlrev_b32_e32 v64, 16, v146
	v_and_b32_e32 v65, 0xffff0000, v146
	v_lshlrev_b32_e32 v66, 16, v234
	v_and_b32_e32 v67, 0xffff0000, v234
	v_lshlrev_b32_e32 v248, 16, v130
	v_and_b32_e32 v249, 0xffff0000, v130
	v_pk_fma_f32 v[248:249], v[64:65], v[248:249], v[66:67]
	s_nop 0
	v_cvt_pk_bf16_f32 v234, v248, v249
	v_lshlrev_b32_e32 v64, 16, v147
	v_and_b32_e32 v65, 0xffff0000, v147
	v_lshlrev_b32_e32 v66, 16, v235
	v_and_b32_e32 v67, 0xffff0000, v235
	v_lshlrev_b32_e32 v248, 16, v131
	v_and_b32_e32 v249, 0xffff0000, v131
	v_pk_fma_f32 v[248:249], v[64:65], v[248:249], v[66:67]
	s_nop 0
	v_cvt_pk_bf16_f32 v235, v248, v249
	global_store_dwordx4 v[244:245], v[232:235], off
	s_waitcnt vmcnt(7) lgkmcnt(0)
	v_lshlrev_b32_e32 v64, 16, v148
	v_and_b32_e32 v65, 0xffff0000, v148
	v_lshlrev_b32_e32 v66, 16, v236
	v_and_b32_e32 v67, 0xffff0000, v236
	v_lshlrev_b32_e32 v248, 16, v140
	v_and_b32_e32 v249, 0xffff0000, v140
	v_pk_fma_f32 v[248:249], v[64:65], v[248:249], v[66:67]
	s_nop 0
	v_cvt_pk_bf16_f32 v236, v248, v249
	v_lshlrev_b32_e32 v64, 16, v149
	v_and_b32_e32 v65, 0xffff0000, v149
	v_lshlrev_b32_e32 v66, 16, v237
	v_and_b32_e32 v67, 0xffff0000, v237
	v_lshlrev_b32_e32 v248, 16, v141
	v_and_b32_e32 v249, 0xffff0000, v141
	v_pk_fma_f32 v[248:249], v[64:65], v[248:249], v[66:67]
	s_nop 0
	v_cvt_pk_bf16_f32 v237, v248, v249
	v_lshlrev_b32_e32 v64, 16, v150
	v_and_b32_e32 v65, 0xffff0000, v150
	v_lshlrev_b32_e32 v66, 16, v238
	v_and_b32_e32 v67, 0xffff0000, v238
	v_lshlrev_b32_e32 v248, 16, v142
	v_and_b32_e32 v249, 0xffff0000, v142
	v_pk_fma_f32 v[248:249], v[64:65], v[248:249], v[66:67]
	s_nop 0
	v_cvt_pk_bf16_f32 v238, v248, v249
	v_lshlrev_b32_e32 v64, 16, v151
	v_and_b32_e32 v65, 0xffff0000, v151
	v_lshlrev_b32_e32 v66, 16, v239
	v_and_b32_e32 v67, 0xffff0000, v239
	v_lshlrev_b32_e32 v248, 16, v143
	v_and_b32_e32 v249, 0xffff0000, v143
	v_pk_fma_f32 v[248:249], v[64:65], v[248:249], v[66:67]
	s_nop 0
	v_cvt_pk_bf16_f32 v239, v248, v249
	global_store_dwordx4 v[246:247], v[236:239], off
	s_branch .LBB0_65
; DI unsigned pk2(float a, float b) { f32x2 v = {a, b}; return __builtin_bit_cast(unsigned, __builtin_convertvector(v, bf16x2)); }
; DI float bflo(unsigned u) { return __uint_as_float(u << 16); }
; DI float bfhi(unsigned u) { return __uint_as_float(u & 0xffff0000u); }
; DI void phase_merge(const Params& P, int layer, char* smem) {
;     ...
; #pragma unroll 2
;         for (int i = 0; i < 8; ++i) {
;           const int idx = tid_ + 256 * i;
;           const int row = idx >> 4, c8 = (idx & 15) * 8;
;           u32x4* gp = (u32x4*)(MG + (size_t)(m0 + row) * 1024 + n0 + c8);
;           const u32x4 mg = *gp;
;           const u32x4 pj = *(const u32x4*)(Cs + row * 136 + c8);
;           u32x4 ov;
;           if (step == 2) {
; #pragma unroll
;             for (int e = 0; e < 4; ++e) ov[e] = pk2(bflo(mg[e]) * bflo(pj[e]), bfhi(mg[e]) * bfhi(pj[e]));
;           } else {
;             const u32x4 tg = *(const u32x4*)(TG + (size_t)(m0 + row) * 1024 + n0 + c8);
; #pragma unroll
;             for (int e = 0; e < 4; ++e) ov[e] = pk2(bflo(mg[e]) + bflo(tg[e]) * bflo(pj[e]), bfhi(mg[e]) + bfhi(tg[e]) * bfhi(pj[e]));
;           }
;           *gp = ov;
;         }
.Lmg_step2:
	ds_read_b128 v[72:75], v65
	ds_read_b128 v[76:79], v65 offset:4352
	ds_read_b128 v[80:83], v65 offset:8704
	ds_read_b128 v[84:87], v65 offset:13056
	ds_read_b128 v[88:91], v65 offset:17408
	ds_read_b128 v[92:95], v65 offset:21760
	ds_read_b128 v[144:147], v65 offset:26112
	ds_read_b128 v[148:151], v65 offset:30464
	s_waitcnt vmcnt(7) lgkmcnt(7)
	v_lshlrev_b32_e32 v64, 16, v72
	v_and_b32_e32 v65, 0xffff0000, v72
	v_lshlrev_b32_e32 v66, 16, v208
	v_and_b32_e32 v67, 0xffff0000, v208
	v_pk_mul_f32 v[66:67], v[66:67], v[64:65]
	s_nop 0
	v_cvt_pk_bf16_f32 v208, v66, v67
	v_lshlrev_b32_e32 v64, 16, v73
	v_and_b32_e32 v65, 0xffff0000, v73
	v_lshlrev_b32_e32 v66, 16, v209
	v_and_b32_e32 v67, 0xffff0000, v209
	v_pk_mul_f32 v[66:67], v[66:67], v[64:65]
	s_nop 0
	v_cvt_pk_bf16_f32 v209, v66, v67
	v_lshlrev_b32_e32 v64, 16, v74
	v_and_b32_e32 v65, 0xffff0000, v74
	v_lshlrev_b32_e32 v66, 16, v210
	v_and_b32_e32 v67, 0xffff0000, v210
	v_pk_mul_f32 v[66:67], v[66:67], v[64:65]
	s_nop 0
	v_cvt_pk_bf16_f32 v210, v66, v67
	v_lshlrev_b32_e32 v64, 16, v75
	v_and_b32_e32 v65, 0xffff0000, v75
	v_lshlrev_b32_e32 v66, 16, v211
	v_and_b32_e32 v67, 0xffff0000, v211
	v_pk_mul_f32 v[66:67], v[66:67], v[64:65]
	s_nop 0
	v_cvt_pk_bf16_f32 v211, v66, v67
	global_store_dwordx4 v[152:153], v[208:211], off
	s_waitcnt vmcnt(7) lgkmcnt(6)
	v_lshlrev_b32_e32 v64, 16, v76
	v_and_b32_e32 v65, 0xffff0000, v76
	v_lshlrev_b32_e32 v66, 16, v212
	v_and_b32_e32 v67, 0xffff0000, v212
	v_pk_mul_f32 v[66:67], v[66:67], v[64:65]
	s_nop 0
	v_cvt_pk_bf16_f32 v212, v66, v67
	v_lshlrev_b32_e32 v64, 16, v77
	v_and_b32_e32 v65, 0xffff0000, v77
	v_lshlrev_b32_e32 v66, 16, v213
	v_and_b32_e32 v67, 0xffff0000, v213
	v_pk_mul_f32 v[66:67], v[66:67], v[64:65]
	s_nop 0
	v_cvt_pk_bf16_f32 v213, v66, v67
	v_lshlrev_b32_e32 v64, 16, v78
	v_and_b32_e32 v65, 0xffff0000, v78
	v_lshlrev_b32_e32 v66, 16, v214
	v_and_b32_e32 v67, 0xffff0000, v214
	v_pk_mul_f32 v[66:67], v[66:67], v[64:65]
	s_nop 0
	v_cvt_pk_bf16_f32 v214, v66, v67
	v_lshlrev_b32_e32 v64, 16, v79
	v_and_b32_e32 v65, 0xffff0000, v79
	v_lshlrev_b32_e32 v66, 16, v215
	v_and_b32_e32 v67, 0xffff0000, v215
	v_pk_mul_f32 v[66:67], v[66:67], v[64:65]
	s_nop 0
	v_cvt_pk_bf16_f32 v215, v66, v67
	global_store_dwordx4 v[154:155], v[212:215], off
	s_waitcnt vmcnt(7) lgkmcnt(5)
	v_lshlrev_b32_e32 v64, 16, v80
	v_and_b32_e32 v65, 0xffff0000, v80
	v_lshlrev_b32_e32 v66, 16, v216
	v_and_b32_e32 v67, 0xffff0000, v216
	v_pk_mul_f32 v[66:67], v[66:67], v[64:65]
	s_nop 0
	v_cvt_pk_bf16_f32 v216, v66, v67
	v_lshlrev_b32_e32 v64, 16, v81
	v_and_b32_e32 v65, 0xffff0000, v81
	v_lshlrev_b32_e32 v66, 16, v217
	v_and_b32_e32 v67, 0xffff0000, v217
	v_pk_mul_f32 v[66:67], v[66:67], v[64:65]
	s_nop 0
	v_cvt_pk_bf16_f32 v217, v66, v67
	v_lshlrev_b32_e32 v64, 16, v82
	v_and_b32_e32 v65, 0xffff0000, v82
	v_lshlrev_b32_e32 v66, 16, v218
	v_and_b32_e32 v67, 0xffff0000, v218
	v_pk_mul_f32 v[66:67], v[66:67], v[64:65]
	s_nop 0
	v_cvt_pk_bf16_f32 v218, v66, v67
	v_lshlrev_b32_e32 v64, 16, v83
	v_and_b32_e32 v65, 0xffff0000, v83
	v_lshlrev_b32_e32 v66, 16, v219
	v_and_b32_e32 v67, 0xffff0000, v219
	v_pk_mul_f32 v[66:67], v[66:67], v[64:65]
	s_nop 0
	v_cvt_pk_bf16_f32 v219, v66, v67
	global_store_dwordx4 v[156:157], v[216:219], off
	s_waitcnt vmcnt(7) lgkmcnt(4)
	v_lshlrev_b32_e32 v64, 16, v84
	v_and_b32_e32 v65, 0xffff0000, v84
	v_lshlrev_b32_e32 v66, 16, v220
	v_and_b32_e32 v67, 0xffff0000, v220
	v_pk_mul_f32 v[66:67], v[66:67], v[64:65]
	s_nop 0
	v_cvt_pk_bf16_f32 v220, v66, v67
	v_lshlrev_b32_e32 v64, 16, v85
	v_and_b32_e32 v65, 0xffff0000, v85
	v_lshlrev_b32_e32 v66, 16, v221
	v_and_b32_e32 v67, 0xffff0000, v221
	v_pk_mul_f32 v[66:67], v[66:67], v[64:65]
	s_nop 0
	v_cvt_pk_bf16_f32 v221, v66, v67
	v_lshlrev_b32_e32 v64, 16, v86
	v_and_b32_e32 v65, 0xffff0000, v86
	v_lshlrev_b32_e32 v66, 16, v222
	v_and_b32_e32 v67, 0xffff0000, v222
	v_pk_mul_f32 v[66:67], v[66:67], v[64:65]
	s_nop 0
	v_cvt_pk_bf16_f32 v222, v66, v67
	v_lshlrev_b32_e32 v64, 16, v87
	v_and_b32_e32 v65, 0xffff0000, v87
	v_lshlrev_b32_e32 v66, 16, v223
	v_and_b32_e32 v67, 0xffff0000, v223
	v_pk_mul_f32 v[66:67], v[66:67], v[64:65]
	s_nop 0
	v_cvt_pk_bf16_f32 v223, v66, v67
	global_store_dwordx4 v[158:159], v[220:223], off
	s_waitcnt vmcnt(7) lgkmcnt(3)
; DI unsigned pk2(float a, float b) { f32x2 v = {a, b}; return __builtin_bit_cast(unsigned, __builtin_convertvector(v, bf16x2)); }
; DI float bflo(unsigned u) { return __uint_as_float(u << 16); }
; DI float bfhi(unsigned u) { return __uint_as_float(u & 0xffff0000u); }
; DI void phase_merge(const Params& P, int layer, char* smem) {
;     ...
;         for (int i = 0; i < 8; ++i) {
;           const int idx = tid_ + 256 * i;
;           const int row = idx >> 4, c8 = (idx & 15) * 8;
;           u32x4* gp = (u32x4*)(MG + (size_t)(m0 + row) * 1024 + n0 + c8);
;           const u32x4 mg = *gp;
;           const u32x4 pj = *(const u32x4*)(Cs + row * 136 + c8);
;           u32x4 ov;
;           if (step == 2) {
; #pragma unroll
;             for (int e = 0; e < 4; ++e) ov[e] = pk2(bflo(mg[e]) * bflo(pj[e]), bfhi(mg[e]) * bfhi(pj[e]));
;           } else {
;             const u32x4 tg = *(const u32x4*)(TG + (size_t)(m0 + row) * 1024 + n0 + c8);
; #pragma unroll
;             for (int e = 0; e < 4; ++e) ov[e] = pk2(bflo(mg[e]) + bflo(tg[e]) * bflo(pj[e]), bfhi(mg[e]) + bfhi(tg[e]) * bfhi(pj[e]));
;           }
;           *gp = ov;
;         }
	v_lshlrev_b32_e32 v64, 16, v88
	v_and_b32_e32 v65, 0xffff0000, v88
	v_lshlrev_b32_e32 v66, 16, v224
	v_and_b32_e32 v67, 0xffff0000, v224
	v_pk_mul_f32 v[66:67], v[66:67], v[64:65]
	s_nop 0
	v_cvt_pk_bf16_f32 v224, v66, v67
	v_lshlrev_b32_e32 v64, 16, v89
	v_and_b32_e32 v65, 0xffff0000, v89
	v_lshlrev_b32_e32 v66, 16, v225
	v_and_b32_e32 v67, 0xffff0000, v225
	v_pk_mul_f32 v[66:67], v[66:67], v[64:65]
	s_nop 0
	v_cvt_pk_bf16_f32 v225, v66, v67
	v_lshlrev_b32_e32 v64, 16, v90
	v_and_b32_e32 v65, 0xffff0000, v90
	v_lshlrev_b32_e32 v66, 16, v226
	v_and_b32_e32 v67, 0xffff0000, v226
	v_pk_mul_f32 v[66:67], v[66:67], v[64:65]
	s_nop 0
	v_cvt_pk_bf16_f32 v226, v66, v67
	v_lshlrev_b32_e32 v64, 16, v91
	v_and_b32_e32 v65, 0xffff0000, v91
	v_lshlrev_b32_e32 v66, 16, v227
	v_and_b32_e32 v67, 0xffff0000, v227
	v_pk_mul_f32 v[66:67], v[66:67], v[64:65]
	s_nop 0
	v_cvt_pk_bf16_f32 v227, v66, v67
	global_store_dwordx4 v[240:241], v[224:227], off
	s_waitcnt vmcnt(7) lgkmcnt(2)
	v_lshlrev_b32_e32 v64, 16, v92
	v_and_b32_e32 v65, 0xffff0000, v92
	v_lshlrev_b32_e32 v66, 16, v228
	v_and_b32_e32 v67, 0xffff0000, v228
	v_pk_mul_f32 v[66:67], v[66:67], v[64:65]
	s_nop 0
	v_cvt_pk_bf16_f32 v228, v66, v67
	v_lshlrev_b32_e32 v64, 16, v93
	v_and_b32_e32 v65, 0xffff0000, v93
	v_lshlrev_b32_e32 v66, 16, v229
	v_and_b32_e32 v67, 0xffff0000, v229
	v_pk_mul_f32 v[66:67], v[66:67], v[64:65]
	s_nop 0
	v_cvt_pk_bf16_f32 v229, v66, v67
	v_lshlrev_b32_e32 v64, 16, v94
	v_and_b32_e32 v65, 0xffff0000, v94
	v_lshlrev_b32_e32 v66, 16, v230
	v_and_b32_e32 v67, 0xffff0000, v230
	v_pk_mul_f32 v[66:67], v[66:67], v[64:65]
	s_nop 0
	v_cvt_pk_bf16_f32 v230, v66, v67
	v_lshlrev_b32_e32 v64, 16, v95
	v_and_b32_e32 v65, 0xffff0000, v95
	v_lshlrev_b32_e32 v66, 16, v231
	v_and_b32_e32 v67, 0xffff0000, v231
	v_pk_mul_f32 v[66:67], v[66:67], v[64:65]
	s_nop 0
	v_cvt_pk_bf16_f32 v231, v66, v67
	global_store_dwordx4 v[242:243], v[228:231], off
	s_waitcnt vmcnt(7) lgkmcnt(1)
	v_lshlrev_b32_e32 v64, 16, v144
	v_and_b32_e32 v65, 0xffff0000, v144
	v_lshlrev_b32_e32 v66, 16, v232
	v_and_b32_e32 v67, 0xffff0000, v232
	v_pk_mul_f32 v[66:67], v[66:67], v[64:65]
	s_nop 0
	v_cvt_pk_bf16_f32 v232, v66, v67
	v_lshlrev_b32_e32 v64, 16, v145
	v_and_b32_e32 v65, 0xffff0000, v145
	v_lshlrev_b32_e32 v66, 16, v233
	v_and_b32_e32 v67, 0xffff0000, v233
	v_pk_mul_f32 v[66:67], v[66:67], v[64:65]
	s_nop 0
	v_cvt_pk_bf16_f32 v233, v66, v67
	v_lshlrev_b32_e32 v64, 16, v146
	v_and_b32_e32 v65, 0xffff0000, v146
	v_lshlrev_b32_e32 v66, 16, v234
	v_and_b32_e32 v67, 0xffff0000, v234
	v_pk_mul_f32 v[66:67], v[66:67], v[64:65]
	s_nop 0
	v_cvt_pk_bf16_f32 v234, v66, v67
	v_lshlrev_b32_e32 v64, 16, v147
	v_and_b32_e32 v65, 0xffff0000, v147
	v_lshlrev_b32_e32 v66, 16, v235
	v_and_b32_e32 v67, 0xffff0000, v235
	v_pk_mul_f32 v[66:67], v[66:67], v[64:65]
	s_nop 0
	v_cvt_pk_bf16_f32 v235, v66, v67
	global_store_dwordx4 v[244:245], v[232:235], off
	s_waitcnt vmcnt(7) lgkmcnt(0)
	v_lshlrev_b32_e32 v64, 16, v148
	v_and_b32_e32 v65, 0xffff0000, v148
	v_lshlrev_b32_e32 v66, 16, v236
	v_and_b32_e32 v67, 0xffff0000, v236
	v_pk_mul_f32 v[66:67], v[66:67], v[64:65]
	s_nop 0
	v_cvt_pk_bf16_f32 v236, v66, v67
	v_lshlrev_b32_e32 v64, 16, v149
	v_and_b32_e32 v65, 0xffff0000, v149
	v_lshlrev_b32_e32 v66, 16, v237
	v_and_b32_e32 v67, 0xffff0000, v237
	v_pk_mul_f32 v[66:67], v[66:67], v[64:65]
	s_nop 0
	v_cvt_pk_bf16_f32 v237, v66, v67
	v_lshlrev_b32_e32 v64, 16, v150
	v_and_b32_e32 v65, 0xffff0000, v150
	v_lshlrev_b32_e32 v66, 16, v238
	v_and_b32_e32 v67, 0xffff0000, v238
	v_pk_mul_f32 v[66:67], v[66:67], v[64:65]
	s_nop 0
	v_cvt_pk_bf16_f32 v238, v66, v67
	v_lshlrev_b32_e32 v64, 16, v151
	v_and_b32_e32 v65, 0xffff0000, v151
	v_lshlrev_b32_e32 v66, 16, v239
	v_and_b32_e32 v67, 0xffff0000, v239
	v_pk_mul_f32 v[66:67], v[66:67], v[64:65]
	s_nop 0
	v_cvt_pk_bf16_f32 v239, v66, v67
	global_store_dwordx4 v[246:247], v[236:239], off
	s_branch .LBB0_65
